# diff-attn: waves 4-7 run a rotated loop body (QK first, barrier after PV2) so SIMD partners are a third of an iteration apart; V ks3 fragments read in PV2 gaps
# speedup vs baseline: 1.0009x; 1.0009x over previous
; #define LAS __attribute__((address_space(3)))
; template <int MODE, bool FROZEN = false>
; __device__ __forceinline__ bool attn_unit(LAS unsigned char* lds, const Params& p, int l, int ua, int ub) {
;     ...
;     for (int t = 0; t < NT; ++t) {
;         if (t + 2 < NT) {
; #pragma unroll
;             for (int i = 0; i < NKC; ++i) *(LAS u32x4*)(lds + kdst[i] + (t & 1) * KBUF) = kr[i];
;         }
;         if (t + 1 < NT) {
; #pragma unroll
;             for (int i = 0; i < NVC; ++i) { *(LAS u32x2*)(lds + vdst[i] + ((t + 1) & 1) * VBUF) = (u32x2){vr[i].x, vr[i].y}; *(LAS u32x2*)(lds + vdst[i] + ((t + 1) & 1) * VBUF + 16) = (u32x2){vr[i].z, vr[i].w}; }
;         }
;         {
;             const size_t advk = (size_t)min(t + 3, NT - 1) * 64 * NPROJ, advv = (size_t)min(t + 2, NT - 1) * 64;
; #pragma unroll
;             for (int i = 0; i < NKC; ++i) kr[i] = *(const u32x4*)(kvbase + advk + ksrc[i]);
; #pragma unroll
;             for (int i = 0; i < NVC; ++i) vr[i] = *(const u32x4*)(vtbase + advv + vsrc[i]);
;         }
;         f32x16 sA0 = sB0, sA1 = sB1;
;         const float c2 = cbB - m_run;
;         const LAS unsigned char* Vb = lds + OFF_V + (t & 1) * VBUF + vlane_off;
;         const LAS unsigned char* Kb = lds + OFF_K + ((t + 1) & 1) * KBUF + klane_off;
.LBB0_117:
	s_cmp_ge_u32 s98, 0x2000
	s_cbranch_scc1 .Ly_entry

; #define LAS __attribute__((address_space(3)))
; template <int MODE, bool FROZEN = false>
; __device__ __forceinline__ bool attn_unit(LAS unsigned char* lds, const Params& p, int l, int ua, int ub) {
;     ...
;     for (int t = 0; t < NT; ++t) {
;         if (t + 2 < NT) {
; #pragma unroll
;             for (int i = 0; i < NKC; ++i) *(LAS u32x4*)(lds + kdst[i] + (t & 1) * KBUF) = kr[i];
;         }
;         if (t + 1 < NT) {
; #pragma unroll
;             for (int i = 0; i < NVC; ++i) { *(LAS u32x2*)(lds + vdst[i] + ((t + 1) & 1) * VBUF) = (u32x2){vr[i].x, vr[i].y}; *(LAS u32x2*)(lds + vdst[i] + ((t + 1) & 1) * VBUF + 16) = (u32x2){vr[i].z, vr[i].w}; }
;         }
;         {
;             const size_t advk = (size_t)min(t + 3, NT - 1) * 64 * NPROJ, advv = (size_t)min(t + 2, NT - 1) * 64;
; #pragma unroll
;             for (int i = 0; i < NKC; ++i) kr[i] = *(const u32x4*)(kvbase + advk + ksrc[i]);
; #pragma unroll
;             for (int i = 0; i < NVC; ++i) vr[i] = *(const u32x4*)(vtbase + advv + vsrc[i]);
;         }
;         f32x16 sA0 = sB0, sA1 = sB1;
;         const float c2 = cbB - m_run;
;         const LAS unsigned char* Vb = lds + OFF_V + (t & 1) * VBUF + vlane_off;
;         const LAS unsigned char* Kb = lds + OFF_K + ((t + 1) & 1) * KBUF + klane_off;
.Ly_entry:
	s_add_i32 s14, s4, 1
	s_bitcmp1_b32 s14, 0
	s_cselect_b32 s15, 0x4400, 0
	s_cselect_b32 s100, 0, 0x4800
	v_add_u32_e32 v194, s100, v101
	s_sub_i32 s5, 0x4400, s15
	s_min_i32 s10, s4, 0xfd
	s_mul_i32 s10, s10, 0x78000
	s_add_u32 s10, s34, s10
	s_addc_u32 s11, s35, 0
	s_add_u32 s10, s10, s99
	s_addc_u32 s11, s11, 0
	s_lshl_b32 s0, s14, 7
	s_add_u32 s0, s6, s0
	s_addc_u32 s1, s7, 0
	s_add_u32 s0, s0, s101
	s_addc_u32 s1, s1, 0
	ds_read_b128 v[112:115], v194 offset:34816
	ds_read_b128 v[170:173], v194 offset:39424
	ds_read_b128 v[174:177], v194 offset:44032
	ds_read_b128 v[178:181], v194 offset:48640
	s_add_i32 m0, s5, s98
	s_nop 0
	global_load_lds_dwordx4 v132, s[10:11]
	s_add_i32 m0, m0, 0x400
	s_nop 0
	global_load_lds_dwordx4 v133, s[10:11]
	s_cmp_lg_u32 s98, 0
	s_cbranch_scc1 .Lkdma_skipye
	s_add_i32 m0, s5, 0x4000
	s_nop 0
	global_load_lds_dwordx4 v134, s[10:11]
.Lkdma_skipye:
	s_sub_i32 s10, 0xd000, s100
	s_add_i32 m0, s10, s98
	s_nop 0
	global_load_lds_dwordx4 v135, s[0:1]
	s_add_i32 m0, m0, 0x400
	s_nop 0
	global_load_lds_dwordx4 v136, s[0:1]
	s_cmp_gt_u32 s98, 0x800
	s_cbranch_scc1 .Lvdma_skipye
	s_lshr_b32 s11, s98, 1
	s_add_i32 s11, s11, s10
	s_add_i32 m0, s11, 0x4000
	s_nop 0
	global_load_lds_dwordx4 v137, s[0:1]

; #define ATT_MAX3(dst) do { float tm_ = max3f(sB0[0], sB1[0], sB0[1]), tn_ = max3f(sB1[1], sB0[2], sB1[2]); \
;         _Pragma("unroll") for (int r = 3; r < 15; r += 2) { tm_ = max3f(tm_, sB0[r], sB1[r]); tn_ = max3f(tn_, sB0[r + 1], sB1[r + 1]); } \
;         tm_ = max3f(tm_, sB0[15], sB1[15]); dst = max3f(tm_, tn_, tn_); } while (0)
; #define VLOAD(ks, DST) do { const LAS unsigned char* vp_ = Vb + (ks) * 32; \
;         _Pragma("unroll") for (int nb = 0; nb < NB; ++nb) DST[nb] = *(const LAS bf16x8*)(vp_ + nb * 32 * VTP); } while (0)
; #define PVMMA(SRC, PF) do { _Pragma("unroll") for (int nb = 0; nb < NB; ++nb) o[nb] = __builtin_amdgcn_mfma_f32_32x32x16_bf16(SRC[nb], PF, o[nb], 0, 0, 0); } while (0)
; #define SBAR_() __builtin_amdgcn_sched_barrier(0)
; template <int MODE, bool FROZEN = false>
; __device__ __forceinline__ bool attn_unit(LAS unsigned char* lds, const Params& p, int l, int ua, int ub) {
;     ...
;         PVMMA(vb, pf1); EXPCVT(2, pf0, ps2); _Pragma("unroll") for (int g_ = 0; g_ < NB; ++g_) { __builtin_amdgcn_sched_group_barrier(0x008, 1, 0); __builtin_amdgcn_sched_group_barrier(0x100, 1, 0); __builtin_amdgcn_sched_group_barrier(0x400, 8 / NB, 0); __builtin_amdgcn_sched_group_barrier(0x002, 12 / NB, 0); } SBAR_();
;         {
;             f32x16 z0, z1;
; #pragma unroll
;             for (int r = 0; r < 16; ++r) { z0[r] = 0.f; z1[r] = 0.f; }
; #pragma unroll
;             for (int d0 = 0; d0 < 4; ++d0) { z0 = __builtin_amdgcn_mfma_f32_32x32x16_bf16(kf0[d0], qf[d0], z0, 0, 0, 0); z1 = __builtin_amdgcn_mfma_f32_32x32x16_bf16(kf1[d0], qf[d0], z1, 0, 0, 0); }
;             sB0 = z0; sB1 = z1;
;         }
;         EXPCVT(3, pf1, ps3);
; #pragma unroll
;         for (int g_ = 0; g_ < 8; ++g_) { __builtin_amdgcn_sched_group_barrier(0x008, 1, 0); __builtin_amdgcn_sched_group_barrier(0x400, 1, 0); __builtin_amdgcn_sched_group_barrier(0x002, 2, 0); }
;         SBAR_();
;         float tmr;
;         VLOAD(3, vb); SBAR_();
;         PVMMA(va, pf0); if constexpr (!FROZEN) ATT_MAX3(tmr); else tmr = 0.f; PVMMA(vb, pf1);
;         const float ps = (ps0 + ps1) + (ps2 + ps3);
.Ly_loop:
	s_add_i32 s14, s4, 1
	s_bitcmp1_b32 s14, 0
	s_cselect_b32 s15, 0x4400, 0
	s_cselect_b32 s100, 0, 0x4800
	v_add_u32_e32 v194, s100, v101
	s_sub_i32 s5, 0x4400, s15
	s_min_i32 s10, s4, 0xfd
	s_mul_i32 s10, s10, 0x78000
	s_add_u32 s10, s34, s10
	s_addc_u32 s11, s35, 0
	s_add_u32 s10, s10, s99
	s_addc_u32 s11, s11, 0
	s_lshl_b32 s0, s14, 7
	s_add_u32 s0, s6, s0
	s_addc_u32 s1, s7, 0
	s_add_u32 s0, s0, s101
	s_addc_u32 s1, s1, 0
	v_mfma_f32_32x32x16_bf16 v[0:15], v[0:3], v[116:119], 0
	v_add_f32_e32 v105, v105, v106
	v_add_f32_e32 v106, v107, v108
	v_add_f32_e32 v107, v109, v110
	v_add_f32_e32 v103, v103, v104
	s_add_i32 m0, s5, s98
	s_nop 0
	global_load_lds_dwordx4 v132, s[10:11]
	v_mfma_f32_32x32x16_bf16 v[0:15], v[20:23], v[120:123], v[0:15]
	v_add_f32_e32 v106, v106, v107
	v_add_f32_e32 v103, v103, v105
	v_add_f32_e32 v105, v115, v170
	v_add_f32_e32 v107, v171, v172
	s_add_i32 m0, m0, 0x400
	s_nop 0
	global_load_lds_dwordx4 v133, s[10:11]
	v_mfma_f32_32x32x16_bf16 v[0:15], v[24:27], v[124:127], v[0:15]
	v_add_f32_e32 v104, v113, v114
	v_add_f32_e32 v105, v105, v107
	v_add_f32_e32 v107, v111, v112
	v_add_f32_e32 v104, v107, v104
	s_cmp_lg_u32 s98, 0
	s_cbranch_scc1 .Lkdma_skipy
	s_add_i32 m0, s5, 0x4000
	s_nop 0
	global_load_lds_dwordx4 v134, s[10:11]
.Lkdma_skipy:
	ds_read_b128 v[112:115], v194 offset:34816
	v_mfma_f32_32x32x16_bf16 v[0:15], v[28:31], v[128:131], v[0:15]
	v_add_f32_e32 v107, v177, v178
	v_add_f32_e32 v108, v179, v180
	v_add_f32_e32 v104, v104, v105
	v_add_f32_e32 v105, v175, v176
	v_mfma_f32_32x32x16_bf16 v[16:31], v[16:19], v[116:119], 0
	v_add_f32_e32 v107, v107, v108
	v_add_f32_e32 v108, v173, v174
	v_add_f32_e32 v105, v108, v105
	v_add_f32_e32 v105, v105, v107
	s_sub_i32 s10, 0xd000, s100
	s_add_i32 m0, s10, s98
	s_nop 0
	global_load_lds_dwordx4 v135, s[0:1]
	ds_read_b128 v[170:173], v194 offset:39424
	ds_read_b128 v[174:177], v194 offset:44032
	v_mfma_f32_32x32x16_bf16 v[16:31], v[218:221], v[120:123], v[16:31]
	v_add_f32_e32 v107, v185, v186
	v_add_f32_e32 v108, v187, v188
	v_add_f32_e32 v103, v103, v106
	v_add_f32_e32 v106, v183, v184
	s_add_i32 m0, m0, 0x400
	s_nop 0
	global_load_lds_dwordx4 v136, s[0:1]
	v_mfma_f32_32x32x16_bf16 v[16:31], v[222:225], v[124:127], v[16:31]
	v_add_f32_e32 v107, v107, v108
	v_add_f32_e32 v108, v181, v182
	v_add_f32_e32 v106, v108, v106
	v_add_f32_e32 v106, v106, v107
	s_cmp_gt_u32 s98, 0x800
	s_cbranch_scc1 .Lvdma_skipy
	s_lshr_b32 s11, s98, 1
	s_add_i32 s11, s11, s10
	s_add_i32 m0, s11, 0x4000
	s_nop 0
	global_load_lds_dwordx4 v137, s[0:1]
.Lvdma_skipy:
	ds_read_b128 v[178:181], v194 offset:48640
	v_mfma_f32_32x32x16_bf16 v[16:31], v[248:251], v[128:131], v[16:31]
	v_add_f32_e32 v103, v103, v104
	v_add_f32_e32 v104, v105, v106
	v_add_f32_e32 v103, v103, v104
	v_add_f32_e32 v100, v100, v103
	s_cmpk_gt_i32 s12, 0x7f
	s_cselect_b64 s[0:1], -1, 0
	s_cmpk_gt_i32 s8, 0x7f
	s_cselect_b64 s[4:5], -1, 0
	s_or_b64 s[10:11], s[0:1], s[4:5]
	s_and_b64 vcc, exec, s[10:11]
	s_nop 0
	s_cbranch_vccnz .Ly120
	v_add_u32_e32 v189, s13, v102
	v_add_u32_e32 v190, 0x11c80, v189
	v_add_u32_e32 v192, 0x11c88, v189
	v_add_u32_e32 v194, 0x11ca0, v189
	v_add_u32_e32 v138, 0x11ca8, v189
	ds_read2_b32 v[190:191], v190 offset1:1
	ds_read2_b32 v[192:193], v192 offset1:1
	ds_read2_b32 v[194:195], v194 offset1:1
	ds_read2_b32 v[138:139], v138 offset1:1
	v_add_u32_e32 v140, 0x11cc0, v189
	v_add_u32_e32 v142, 0x11cc8, v189
	v_add_u32_e32 v144, 0x11ce0, v189
	v_add_u32_e32 v146, 0x11ce8, v189
	ds_read2_b32 v[140:141], v140 offset1:1
	ds_read2_b32 v[142:143], v142 offset1:1
	ds_read2_b32 v[144:145], v144 offset1:1
	ds_read2_b32 v[146:147], v146 offset1:1
	s_waitcnt lgkmcnt(7)
	v_sub_f32_e32 v191, v191, v169
	v_sub_f32_e32 v190, v190, v169
	s_waitcnt lgkmcnt(2)
	v_sub_f32_e32 v143, v143, v169
	v_sub_f32_e32 v141, v141, v169
	v_sub_f32_e32 v140, v140, v169
	v_sub_f32_e32 v142, v142, v169
	s_waitcnt lgkmcnt(1)
	v_sub_f32_e32 v145, v145, v169
	v_sub_f32_e32 v144, v144, v169
	s_waitcnt lgkmcnt(0)
	v_sub_f32_e32 v147, v147, v169
	v_sub_f32_e32 v146, v146, v169
	v_sub_f32_e32 v193, v193, v169
	v_sub_f32_e32 v192, v192, v169
	v_sub_f32_e32 v195, v195, v169
	v_sub_f32_e32 v194, v194, v169
	v_sub_f32_e32 v139, v139, v169
	v_sub_f32_e32 v138, v138, v169
	v_pk_add_f32 v[22:23], v[22:23], v[138:139]
	v_pk_add_f32 v[20:21], v[20:21], v[194:195]
	v_pk_add_f32 v[18:19], v[18:19], v[192:193]
	v_pk_add_f32 v[16:17], v[16:17], v[190:191]
	v_pk_add_f32 v[30:31], v[30:31], v[146:147]
	v_pk_add_f32 v[28:29], v[28:29], v[144:145]
	v_pk_add_f32 v[26:27], v[26:27], v[142:143]
	v_pk_add_f32 v[24:25], v[24:25], v[140:141]
	v_add_u32_e32 v190, 0x11d00, v189
	v_add_u32_e32 v192, 0x11d08, v189
	v_add_u32_e32 v194, 0x11d20, v189
	v_add_u32_e32 v138, 0x11d28, v189
	ds_read2_b32 v[190:191], v190 offset1:1
	ds_read2_b32 v[192:193], v192 offset1:1
	ds_read2_b32 v[194:195], v194 offset1:1
	ds_read2_b32 v[138:139], v138 offset1:1
	v_add_u32_e32 v140, 0x11d40, v189
	v_add_u32_e32 v142, 0x11d48, v189
	v_add_u32_e32 v144, 0x11d60, v189
	ds_read2_b32 v[140:141], v140 offset1:1
	v_add_u32_e32 v189, 0x11d68, v189
	ds_read2_b32 v[142:143], v142 offset1:1
	ds_read2_b32 v[144:145], v144 offset1:1
	ds_read2_b32 v[146:147], v189 offset1:1
	s_waitcnt lgkmcnt(7)
	v_sub_f32_e32 v191, v191, v169
	v_sub_f32_e32 v190, v190, v169
	s_waitcnt lgkmcnt(3)
	v_sub_f32_e32 v141, v141, v169
	v_sub_f32_e32 v140, v140, v169
	s_waitcnt lgkmcnt(2)
	v_sub_f32_e32 v143, v143, v169
	v_sub_f32_e32 v142, v142, v169
	s_waitcnt lgkmcnt(1)
	v_sub_f32_e32 v145, v145, v169
	v_sub_f32_e32 v144, v144, v169
	s_waitcnt lgkmcnt(0)
	v_sub_f32_e32 v147, v147, v169
	v_sub_f32_e32 v146, v146, v169
	v_sub_f32_e32 v193, v193, v169
	v_sub_f32_e32 v192, v192, v169
	v_sub_f32_e32 v195, v195, v169
	v_sub_f32_e32 v194, v194, v169
	v_sub_f32_e32 v139, v139, v169
	v_sub_f32_e32 v138, v138, v169
	v_pk_add_f32 v[6:7], v[6:7], v[138:139]
	v_pk_add_f32 v[4:5], v[4:5], v[194:195]
	v_pk_add_f32 v[2:3], v[2:3], v[192:193]
	v_pk_add_f32 v[0:1], v[0:1], v[190:191]
	v_pk_add_f32 v[14:15], v[14:15], v[146:147]
	v_pk_add_f32 v[12:13], v[12:13], v[144:145]
	v_pk_add_f32 v[10:11], v[10:11], v[142:143]
	v_pk_add_f32 v[8:9], v[8:9], v[140:141]

; #define LAS __attribute__((address_space(3)))
; #define VLOAD(ks, DST) do { const LAS unsigned char* vp_ = Vb + (ks) * 32; \
;         _Pragma("unroll") for (int nb = 0; nb < NB; ++nb) DST[nb] = *(const LAS bf16x8*)(vp_ + nb * 32 * VTP); } while (0)
; #define PVMMA(SRC, PF) do { _Pragma("unroll") for (int nb = 0; nb < NB; ++nb) o[nb] = __builtin_amdgcn_mfma_f32_32x32x16_bf16(SRC[nb], PF, o[nb], 0, 0, 0); } while (0)
; #define SBAR_() __builtin_amdgcn_sched_barrier(0)
; template <int MODE, bool FROZEN = false>
; __device__ __forceinline__ bool attn_unit(LAS unsigned char* lds, const Params& p, int l, int ua, int ub) {
;     ...
;         f32x16 sA0 = sB0, sA1 = sB1;
;         const float c2 = cbB - m_run;
;         const LAS unsigned char* Vb = lds + OFF_V + (t & 1) * VBUF + vlane_off;
;         const LAS unsigned char* Kb = lds + OFF_K + ((t + 1) & 1) * KBUF + klane_off;
;     ...
;         bf16x8 kf0[4], kf1[4], va[NB], vb[NB], pf0, pf1; float ps0, ps1, ps2, ps3;
;         VLOAD(0, va);
;         EXPCVT(0, pf0, ps0);
;         SBAR_();
;         VLOAD(1, vb); PVMMA(va, pf0); EXPCVT(1, pf1, ps1); _Pragma("unroll") for (int g_ = 0; g_ < NB; ++g_) { __builtin_amdgcn_sched_group_barrier(0x008, 1, 0); __builtin_amdgcn_sched_group_barrier(0x100, 1, 0); __builtin_amdgcn_sched_group_barrier(0x400, 8 / NB, 0); __builtin_amdgcn_sched_group_barrier(0x002, 12 / NB, 0); } SBAR_();
;         VLOAD(2, va);
; #pragma unroll
;         for (int d0 = 0; d0 < 4; ++d0) { kf0[d0] = *(const LAS bf16x8*)(Kb + d0 * 32); kf1[d0] = *(const LAS bf16x8*)(Kb + 32 * KPB + d0 * 32); }
;         PVMMA(vb, pf1); EXPCVT(2, pf0, ps2); _Pragma("unroll") for (int g_ = 0; g_ < NB; ++g_) { __builtin_amdgcn_sched_group_barrier(0x008, 1, 0); __builtin_amdgcn_sched_group_barrier(0x100, 1, 0); __builtin_amdgcn_sched_group_barrier(0x400, 8 / NB, 0); __builtin_amdgcn_sched_group_barrier(0x002, 12 / NB, 0); } SBAR_();
;     ...
;         asm volatile("s_waitcnt lgkmcnt(0)" ::: "memory"); __builtin_amdgcn_s_barrier(); asm volatile("" ::: "memory");
.Ly123:
	s_addk_i32 s13, 0x100
	s_sub_i32 s8, s8, 64
	s_add_i32 s12, s12, 64
.Ly_pv3:
	v_add_u32_e32 v194, s100, v101
	v_exp_f32_e32 v103, v16
	v_exp_f32_e32 v104, v17
	v_mfma_f32_32x32x16_bf16 v[52:67], v[236:239], v[244:247], v[52:67]
	v_exp_f32_e32 v105, v18
	v_exp_f32_e32 v106, v19
	v_cvt_pk_bf16_f32 v16, v103, v104
	v_mfma_f32_32x32x16_bf16 v[36:51], v[206:209], v[244:247], v[36:51]
	v_exp_f32_e32 v107, v20
	v_exp_f32_e32 v108, v21
	v_cvt_pk_bf16_f32 v17, v105, v106
	v_mfma_f32_32x32x16_bf16 v[84:99], v[210:213], v[244:247], v[84:99]
	v_exp_f32_e32 v109, v22
	v_exp_f32_e32 v110, v23
	v_cvt_pk_bf16_f32 v18, v107, v108
	v_mfma_f32_32x32x16_bf16 v[68:83], v[214:217], v[244:247], v[68:83]
	v_add_u32_e32 v195, s15, v166
	v_cvt_pk_bf16_f32 v19, v109, v110
	s_waitcnt lgkmcnt(3)
	s_nop 0
	v_mfma_f32_32x32x16_bf16 v[36:51], v[112:115], v[16:19], v[36:51]
	ds_read_b128 v[20:23], v194 offset:34848
	ds_read_b128 v[218:221], v195 offset:32
	v_exp_f32_e32 v111, v24
	v_exp_f32_e32 v112, v25
	s_nop 0
	v_cvt_pk_bf16_f32 v24, v111, v112
	s_waitcnt lgkmcnt(4)
	v_mfma_f32_32x32x16_bf16 v[84:99], v[170:173], v[16:19], v[84:99]
	ds_read_b128 v[182:185], v194 offset:39456
	ds_read_b128 v[222:225], v195 offset:64
	v_exp_f32_e32 v113, v26
	v_exp_f32_e32 v114, v27
	s_nop 0
	v_cvt_pk_bf16_f32 v25, v113, v114
	s_waitcnt lgkmcnt(5)
	v_mfma_f32_32x32x16_bf16 v[68:83], v[174:177], v[16:19], v[68:83]
	ds_read_b128 v[186:189], v194 offset:44064
	ds_read_b128 v[248:251], v195 offset:96
	v_exp_f32_e32 v115, v28
	v_exp_f32_e32 v170, v29
	s_nop 0
	v_cvt_pk_bf16_f32 v26, v115, v170
	s_waitcnt lgkmcnt(6)
	v_mfma_f32_32x32x16_bf16 v[52:67], v[178:181], v[16:19], v[52:67]
	ds_read_b128 v[16:19], v194 offset:48672
	v_exp_f32_e32 v171, v30
	v_exp_f32_e32 v172, v31
	s_nop 0
	v_cvt_pk_bf16_f32 v27, v171, v172
	s_waitcnt lgkmcnt(6)
	s_nop 0
	v_mfma_f32_32x32x16_bf16 v[36:51], v[20:23], v[24:27], v[36:51]
	ds_read_b128 v[190:193], v194 offset:34880
	ds_read_b128 v[20:23], v195 offset:8736
	v_exp_f32_e32 v173, v0
	v_exp_f32_e32 v174, v1
	s_nop 0
	v_cvt_pk_bf16_f32 v202, v173, v174
	s_waitcnt lgkmcnt(6)
	v_mfma_f32_32x32x16_bf16 v[84:99], v[182:185], v[24:27], v[84:99]
	ds_read_b128 v[206:209], v194 offset:39488
	v_exp_f32_e32 v175, v2
	v_exp_f32_e32 v176, v3
	s_nop 0
	v_cvt_pk_bf16_f32 v203, v175, v176
	s_waitcnt lgkmcnt(5)
	v_mfma_f32_32x32x16_bf16 v[68:83], v[186:189], v[24:27], v[68:83]
	ds_read_b128 v[210:213], v194 offset:44096
	v_exp_f32_e32 v177, v4
	v_exp_f32_e32 v178, v5
	s_nop 0
	v_cvt_pk_bf16_f32 v204, v177, v178
	s_waitcnt lgkmcnt(4)
	v_mfma_f32_32x32x16_bf16 v[52:67], v[16:19], v[24:27], v[52:67]
	ds_read_b128 v[214:217], v194 offset:48704
	ds_read_b128 v[236:239], v194 offset:48736
	ds_read_b128 v[0:3], v195 offset:8704
	v_exp_f32_e32 v179, v6
	v_exp_f32_e32 v180, v7
	s_nop 0
	v_cvt_pk_bf16_f32 v205, v179, v180
	v_exp_f32_e32 v181, v8
	v_exp_f32_e32 v182, v9
	s_waitcnt lgkmcnt(6)
	v_mfma_f32_32x32x16_bf16 v[36:51], v[190:193], v[202:205], v[36:51]
	ds_read_b128 v[24:27], v195 offset:8768
	v_exp_f32_e32 v183, v10
	v_exp_f32_e32 v184, v11
	v_cvt_pk_bf16_f32 v244, v181, v182
	s_waitcnt lgkmcnt(5)
	v_mfma_f32_32x32x16_bf16 v[84:99], v[206:209], v[202:205], v[84:99]
	ds_read_b128 v[28:31], v195 offset:8800
	ds_read_b128 v[206:209], v194 offset:34912
	v_exp_f32_e32 v185, v12
	v_exp_f32_e32 v186, v13
	v_cvt_pk_bf16_f32 v245, v183, v184
	s_waitcnt lgkmcnt(6)
	v_mfma_f32_32x32x16_bf16 v[68:83], v[210:213], v[202:205], v[68:83]
	ds_read_b128 v[16:19], v195
	ds_read_b128 v[210:213], v194 offset:39520
	v_exp_f32_e32 v187, v14
	v_exp_f32_e32 v188, v15
	v_cvt_pk_bf16_f32 v246, v185, v186
	s_waitcnt lgkmcnt(7)
	v_mfma_f32_32x32x16_bf16 v[52:67], v[214:217], v[202:205], v[52:67]
	ds_read_b128 v[214:217], v194 offset:44128
	v_cvt_pk_bf16_f32 v247, v187, v188
	s_waitcnt vmcnt(0) lgkmcnt(0)
	s_barrier
	s_cmpk_eq_u32 s13, 0xfe00
	s_cbranch_scc1 .Ly_exit
	s_mov_b32 s4, s14
	s_branch .Ly_loop
; #define ATT_MAX3(dst) do { float tm_ = max3f(sB0[0], sB1[0], sB0[1]), tn_ = max3f(sB1[1], sB0[2], sB1[2]); \
;         _Pragma("unroll") for (int r = 3; r < 15; r += 2) { tm_ = max3f(tm_, sB0[r], sB1[r]); tn_ = max3f(tn_, sB0[r + 1], sB1[r + 1]); } \
;         tm_ = max3f(tm_, sB0[15], sB1[15]); dst = max3f(tm_, tn_, tn_); } while (0)
; #define VLOAD(ks, DST) do { const LAS unsigned char* vp_ = Vb + (ks) * 32; \
;         _Pragma("unroll") for (int nb = 0; nb < NB; ++nb) DST[nb] = *(const LAS bf16x8*)(vp_ + nb * 32 * VTP); } while (0)
; #define PVMMA(SRC, PF) do { _Pragma("unroll") for (int nb = 0; nb < NB; ++nb) o[nb] = __builtin_amdgcn_mfma_f32_32x32x16_bf16(SRC[nb], PF, o[nb], 0, 0, 0); } while (0)
; #define SBAR_() __builtin_amdgcn_sched_barrier(0)
; template <int MODE, bool FROZEN = false>
; __device__ __forceinline__ bool attn_unit(LAS unsigned char* lds, const Params& p, int l, int ua, int ub) {
;     ...
; #pragma unroll
;             for (int d0 = 0; d0 < 4; ++d0) { z0 = __builtin_amdgcn_mfma_f32_32x32x16_bf16(kf0[d0], qf[d0], z0, 0, 0, 0); z1 = __builtin_amdgcn_mfma_f32_32x32x16_bf16(kf1[d0], qf[d0], z1, 0, 0, 0); }
;             sB0 = z0; sB1 = z1;
;         }
;         EXPCVT(3, pf1, ps3);
; #pragma unroll
;         for (int g_ = 0; g_ < 8; ++g_) { __builtin_amdgcn_sched_group_barrier(0x008, 1, 0); __builtin_amdgcn_sched_group_barrier(0x400, 1, 0); __builtin_amdgcn_sched_group_barrier(0x002, 2, 0); }
;         SBAR_();
;         float tmr;
;         VLOAD(3, vb); SBAR_();
;         PVMMA(va, pf0); if constexpr (!FROZEN) ATT_MAX3(tmr); else tmr = 0.f; PVMMA(vb, pf1);
;         const float ps = (ps0 + ps1) + (ps2 + ps3);
.Ly_exit:
	v_mfma_f32_32x32x16_bf16 v[0:15], v[0:3], v[116:119], 0
	v_add_f32_e32 v105, v105, v106
	v_add_f32_e32 v106, v107, v108
	v_add_f32_e32 v107, v109, v110
	v_add_f32_e32 v103, v103, v104
	v_mfma_f32_32x32x16_bf16 v[0:15], v[20:23], v[120:123], v[0:15]
	v_add_f32_e32 v106, v106, v107
	v_add_f32_e32 v103, v103, v105
	v_add_f32_e32 v105, v115, v170
	v_add_f32_e32 v107, v171, v172
	v_mfma_f32_32x32x16_bf16 v[0:15], v[24:27], v[124:127], v[0:15]
	v_add_f32_e32 v104, v113, v114
	v_add_f32_e32 v105, v105, v107
	v_add_f32_e32 v107, v111, v112
	v_add_f32_e32 v104, v107, v104
	v_mfma_f32_32x32x16_bf16 v[0:15], v[28:31], v[128:131], v[0:15]
	v_add_f32_e32 v107, v177, v178
	v_add_f32_e32 v108, v179, v180
	v_add_f32_e32 v104, v104, v105
	v_add_f32_e32 v105, v175, v176
	v_mfma_f32_32x32x16_bf16 v[16:31], v[16:19], v[116:119], 0
	v_add_f32_e32 v107, v107, v108
	v_add_f32_e32 v108, v173, v174
	v_add_f32_e32 v105, v108, v105
	v_add_f32_e32 v105, v105, v107
	v_mfma_f32_32x32x16_bf16 v[16:31], v[218:221], v[120:123], v[16:31]
	v_add_f32_e32 v107, v185, v186
	v_add_f32_e32 v108, v187, v188
	v_add_f32_e32 v103, v103, v106
	v_add_f32_e32 v106, v183, v184
	v_mfma_f32_32x32x16_bf16 v[16:31], v[222:225], v[124:127], v[16:31]
	v_add_f32_e32 v107, v107, v108
	v_add_f32_e32 v108, v181, v182
	v_add_f32_e32 v106, v108, v106
	v_add_f32_e32 v106, v106, v107
	v_mfma_f32_32x32x16_bf16 v[16:31], v[248:251], v[128:131], v[16:31]
	v_add_f32_e32 v103, v103, v104
	v_add_f32_e32 v104, v105, v106
	v_add_f32_e32 v103, v103, v104
	v_add_f32_e32 v100, v100, v103
	s_cmpk_gt_i32 s12, 0x7f
	s_cselect_b64 s[0:1], -1, 0
	s_cmpk_gt_i32 s8, 0x7f
	s_cselect_b64 s[4:5], -1, 0
	s_or_b64 s[10:11], s[0:1], s[4:5]
	s_and_b64 vcc, exec, s[10:11]
	s_nop 0
	s_cbranch_vccnz .Lz120
	v_add_u32_e32 v189, s13, v102
	v_add_u32_e32 v190, 0x11c80, v189
	v_add_u32_e32 v192, 0x11c88, v189
	v_add_u32_e32 v194, 0x11ca0, v189
	v_add_u32_e32 v138, 0x11ca8, v189
	ds_read2_b32 v[190:191], v190 offset1:1
	ds_read2_b32 v[192:193], v192 offset1:1
	ds_read2_b32 v[194:195], v194 offset1:1
	ds_read2_b32 v[138:139], v138 offset1:1
	v_add_u32_e32 v140, 0x11cc0, v189
	v_add_u32_e32 v142, 0x11cc8, v189
	v_add_u32_e32 v144, 0x11ce0, v189
	v_add_u32_e32 v146, 0x11ce8, v189
	ds_read2_b32 v[140:141], v140 offset1:1
	ds_read2_b32 v[142:143], v142 offset1:1
	ds_read2_b32 v[144:145], v144 offset1:1
	ds_read2_b32 v[146:147], v146 offset1:1
	s_waitcnt lgkmcnt(7)
	v_sub_f32_e32 v191, v191, v169
	v_sub_f32_e32 v190, v190, v169
	s_waitcnt lgkmcnt(2)
	v_sub_f32_e32 v143, v143, v169
	v_sub_f32_e32 v141, v141, v169
	v_sub_f32_e32 v140, v140, v169
	v_sub_f32_e32 v142, v142, v169
	s_waitcnt lgkmcnt(1)
	v_sub_f32_e32 v145, v145, v169
	v_sub_f32_e32 v144, v144, v169
	s_waitcnt lgkmcnt(0)
	v_sub_f32_e32 v147, v147, v169
	v_sub_f32_e32 v146, v146, v169
	v_sub_f32_e32 v193, v193, v169
	v_sub_f32_e32 v192, v192, v169
	v_sub_f32_e32 v195, v195, v169
	v_sub_f32_e32 v194, v194, v169
	v_sub_f32_e32 v139, v139, v169
	v_sub_f32_e32 v138, v138, v169
	v_pk_add_f32 v[22:23], v[22:23], v[138:139]
	v_pk_add_f32 v[20:21], v[20:21], v[194:195]
	v_pk_add_f32 v[18:19], v[18:19], v[192:193]
	v_pk_add_f32 v[16:17], v[16:17], v[190:191]
	v_pk_add_f32 v[30:31], v[30:31], v[146:147]
	v_pk_add_f32 v[28:29], v[28:29], v[144:145]
	v_pk_add_f32 v[26:27], v[26:27], v[142:143]
	v_pk_add_f32 v[24:25], v[24:25], v[140:141]
	v_add_u32_e32 v190, 0x11d00, v189
	v_add_u32_e32 v192, 0x11d08, v189
	v_add_u32_e32 v194, 0x11d20, v189
	v_add_u32_e32 v138, 0x11d28, v189
	ds_read2_b32 v[190:191], v190 offset1:1
	ds_read2_b32 v[192:193], v192 offset1:1
	ds_read2_b32 v[194:195], v194 offset1:1
	ds_read2_b32 v[138:139], v138 offset1:1
	v_add_u32_e32 v140, 0x11d40, v189
	v_add_u32_e32 v142, 0x11d48, v189
	v_add_u32_e32 v144, 0x11d60, v189
	ds_read2_b32 v[140:141], v140 offset1:1
	v_add_u32_e32 v189, 0x11d68, v189
	ds_read2_b32 v[142:143], v142 offset1:1
	ds_read2_b32 v[144:145], v144 offset1:1
	ds_read2_b32 v[146:147], v189 offset1:1
	s_waitcnt lgkmcnt(7)
	v_sub_f32_e32 v191, v191, v169
	v_sub_f32_e32 v190, v190, v169
	s_waitcnt lgkmcnt(3)
	v_sub_f32_e32 v141, v141, v169
	v_sub_f32_e32 v140, v140, v169
	s_waitcnt lgkmcnt(2)
	v_sub_f32_e32 v143, v143, v169
	v_sub_f32_e32 v142, v142, v169
	s_waitcnt lgkmcnt(1)
	v_sub_f32_e32 v145, v145, v169
	v_sub_f32_e32 v144, v144, v169
	s_waitcnt lgkmcnt(0)
	v_sub_f32_e32 v147, v147, v169
	v_sub_f32_e32 v146, v146, v169
	v_sub_f32_e32 v193, v193, v169
	v_sub_f32_e32 v192, v192, v169
	v_sub_f32_e32 v195, v195, v169
	v_sub_f32_e32 v194, v194, v169
	v_sub_f32_e32 v139, v139, v169
	v_sub_f32_e32 v138, v138, v169
	v_pk_add_f32 v[6:7], v[6:7], v[138:139]
	v_pk_add_f32 v[4:5], v[4:5], v[194:195]
	v_pk_add_f32 v[2:3], v[2:3], v[192:193]
	v_pk_add_f32 v[0:1], v[0:1], v[190:191]
	v_pk_add_f32 v[14:15], v[14:15], v[146:147]
	v_pk_add_f32 v[12:13], v[12:13], v[144:145]
	v_pk_add_f32 v[10:11], v[10:11], v[142:143]
	v_pk_add_f32 v[8:9], v[8:9], v[140:141]

; template <int MODE, bool FROZEN = false>
; __device__ __forceinline__ bool attn_unit(LAS unsigned char* lds, const Params& p, int l, int ua, int ub) {
;     ...
;         VLOAD(0, va);
;         EXPCVT(0, pf0, ps0);
;         SBAR_();
;         VLOAD(1, vb); PVMMA(va, pf0); EXPCVT(1, pf1, ps1); _Pragma("unroll") for (int g_ = 0; g_ < NB; ++g_) { __builtin_amdgcn_sched_group_barrier(0x008, 1, 0); __builtin_amdgcn_sched_group_barrier(0x100, 1, 0); __builtin_amdgcn_sched_group_barrier(0x400, 8 / NB, 0); __builtin_amdgcn_sched_group_barrier(0x002, 12 / NB, 0); } SBAR_();
;         VLOAD(2, va);
; #pragma unroll
;         for (int d0 = 0; d0 < 4; ++d0) { kf0[d0] = *(const LAS bf16x8*)(Kb + d0 * 32); kf1[d0] = *(const LAS bf16x8*)(Kb + 32 * KPB + d0 * 32); }
;         PVMMA(vb, pf1); EXPCVT(2, pf0, ps2); _Pragma("unroll") for (int g_ = 0; g_ < NB; ++g_) { __builtin_amdgcn_sched_group_barrier(0x008, 1, 0); __builtin_amdgcn_sched_group_barrier(0x100, 1, 0); __builtin_amdgcn_sched_group_barrier(0x400, 8 / NB, 0); __builtin_amdgcn_sched_group_barrier(0x002, 12 / NB, 0); } SBAR_();
;         {
;             f32x16 z0, z1;
; #pragma unroll
;             for (int r = 0; r < 16; ++r) { z0[r] = 0.f; z1[r] = 0.f; }
; #pragma unroll
;             for (int d0 = 0; d0 < 4; ++d0) { z0 = __builtin_amdgcn_mfma_f32_32x32x16_bf16(kf0[d0], qf[d0], z0, 0, 0, 0); z1 = __builtin_amdgcn_mfma_f32_32x32x16_bf16(kf1[d0], qf[d0], z1, 0, 0, 0); }
;             sB0 = z0; sB1 = z1;
;         }
;         EXPCVT(3, pf1, ps3);
; #pragma unroll
;         for (int g_ = 0; g_ < 8; ++g_) { __builtin_amdgcn_sched_group_barrier(0x008, 1, 0); __builtin_amdgcn_sched_group_barrier(0x400, 1, 0); __builtin_amdgcn_sched_group_barrier(0x002, 2, 0); }
;         SBAR_();
;         float tmr;
;         VLOAD(3, vb); SBAR_();
;         PVMMA(va, pf0); if constexpr (!FROZEN) ATT_MAX3(tmr); else tmr = 0.f; PVMMA(vb, pf1);
;         const float ps = (ps0 + ps1) + (ps2 + ps3);
;     ...
;         l_run += ps;
;         if (t + 1 < NT) { ATT_BIAS(t + 1, tmr); ATT_UPD(tmr); }
;         asm volatile("s_waitcnt lgkmcnt(0)" ::: "memory"); __builtin_amdgcn_s_barrier(); asm volatile("" ::: "memory");
;     }
;     __syncthreads();
;     ...
;     if constexpr (FROZEN) {
;         const float lt_ = xhalf_sum(l_run); const bool bad_ = !(lt_ > 0x1p-60f && lt_ < 0x1p60f);
;         LAS unsigned* flg_ = (LAS unsigned*)(lds + OFF_LUT + 4096);
.Lz123:
.LBB0_125:
	s_setprio 0
	v_mfma_f32_32x32x16_bf16 v[52:67], v[236:239], v[244:247], v[52:67]
	v_mfma_f32_32x32x16_bf16 v[36:51], v[206:209], v[244:247], v[36:51]
	v_mfma_f32_32x32x16_bf16 v[84:99], v[210:213], v[244:247], v[84:99]
	v_mfma_f32_32x32x16_bf16 v[68:83], v[214:217], v[244:247], v[68:83]
	v_add_u32_e32 v33, 0x8800, v101
	ds_read_b128 v[104:107], v33 offset:32256
	ds_read_b128 v[108:111], v101 offset:62464
	ds_read_b128 v[112:115], v101 offset:57856
	ds_read_b128 v[116:119], v101 offset:53248
	v_exp_f32_e32 v125, v16
	v_exp_f32_e32 v127, v17
	v_exp_f32_e32 v129, v18
	v_exp_f32_e32 v131, v19
	v_exp_f32_e32 v103, v20
	v_exp_f32_e32 v21, v21
	v_exp_f32_e32 v17, v22
	v_exp_f32_e32 v19, v23
	v_cvt_pk_bf16_f32 v120, v125, v127
	v_cvt_pk_bf16_f32 v121, v129, v131
	v_cvt_pk_bf16_f32 v122, v103, v21
	v_cvt_pk_bf16_f32 v123, v17, v19
	s_waitcnt lgkmcnt(0)
	s_nop 0
	v_mfma_f32_32x32x16_bf16 v[36:51], v[116:119], v[120:123], v[36:51]
	ds_read_b128 v[116:119], v101 offset:53280
	s_waitcnt vmcnt(3)
	v_exp_f32_e32 v133, v24
	v_exp_f32_e32 v135, v25
	s_nop 0
	v_cvt_pk_bf16_f32 v22, v133, v135
	v_mfma_f32_32x32x16_bf16 v[84:99], v[112:115], v[120:123], v[84:99]
	ds_read_b128 v[112:115], v101 offset:57888
	s_waitcnt vmcnt(1)
	v_exp_f32_e32 v137, v26
	v_exp_f32_e32 v139, v27
	s_nop 0
	v_cvt_pk_bf16_f32 v23, v137, v139
	v_mfma_f32_32x32x16_bf16 v[68:83], v[108:111], v[120:123], v[68:83]
	ds_read_b128 v[108:111], v101 offset:62496
	v_exp_f32_e32 v141, v28
	v_exp_f32_e32 v143, v29
	s_nop 0
	v_cvt_pk_bf16_f32 v24, v141, v143
	v_mfma_f32_32x32x16_bf16 v[52:67], v[104:107], v[120:123], v[52:67]
	ds_read_b128 v[26:29], v33 offset:32288
	v_exp_f32_e32 v121, v30
	v_exp_f32_e32 v31, v31
	s_nop 0
	v_cvt_pk_bf16_f32 v25, v121, v31
	s_waitcnt lgkmcnt(3)
	s_nop 0
	v_mfma_f32_32x32x16_bf16 v[36:51], v[116:119], v[22:25], v[36:51]
	ds_read_b128 v[104:107], v101 offset:53312
	v_exp_f32_e32 v124, v0
	v_exp_f32_e32 v126, v1
	s_nop 0
	v_cvt_pk_bf16_f32 v0, v124, v126
	s_waitcnt lgkmcnt(3)
	v_mfma_f32_32x32x16_bf16 v[84:99], v[112:115], v[22:25], v[84:99]
	ds_read_b128 v[112:115], v101 offset:57920
	v_exp_f32_e32 v128, v2
	v_exp_f32_e32 v130, v3
	s_nop 0
	v_cvt_pk_bf16_f32 v1, v128, v130
	s_waitcnt lgkmcnt(3)
	v_mfma_f32_32x32x16_bf16 v[68:83], v[108:111], v[22:25], v[68:83]
	ds_read_b128 v[108:111], v101 offset:62528
	v_exp_f32_e32 v102, v4
	v_exp_f32_e32 v20, v5
	s_nop 0
	v_cvt_pk_bf16_f32 v2, v102, v20
	s_waitcnt lgkmcnt(3)
	v_mfma_f32_32x32x16_bf16 v[52:67], v[26:29], v[22:25], v[52:67]
	ds_read_b128 v[22:25], v33 offset:32320
	v_exp_f32_e32 v16, v6
	v_exp_f32_e32 v18, v7
	s_nop 0
	v_cvt_pk_bf16_f32 v3, v16, v18
	v_exp_f32_e32 v132, v8
	v_exp_f32_e32 v134, v9
	s_nop 0
	v_cvt_pk_bf16_f32 v4, v132, v134
	v_exp_f32_e32 v136, v10
	v_exp_f32_e32 v138, v11
	s_nop 0
	v_cvt_pk_bf16_f32 v5, v136, v138
	v_exp_f32_e32 v140, v12
	v_exp_f32_e32 v142, v13
	s_nop 0
	v_cvt_pk_bf16_f32 v6, v140, v142
	v_exp_f32_e32 v120, v14
	v_exp_f32_e32 v30, v15
	s_nop 0
	v_cvt_pk_bf16_f32 v7, v120, v30
	ds_read_b128 v[8:11], v101 offset:53344
	ds_read_b128 v[12:15], v101 offset:57952
	ds_read_b128 v[26:29], v101 offset:62560
	ds_read_b128 v[116:119], v33 offset:32352
	s_waitcnt lgkmcnt(7)
	v_mfma_f32_32x32x16_bf16 v[36:51], v[104:107], v[0:3], v[36:51]
	v_add_f32_e64 v16, v16, v18
	v_add_f32_e64 v17, v17, v19
	s_waitcnt lgkmcnt(0)
	s_barrier
	v_cmp_eq_u32_e32 vcc, 0, v148
	s_waitcnt lgkmcnt(0)
	s_barrier
	v_mfma_f32_32x32x16_bf16 v[84:99], v[112:115], v[0:3], v[84:99]
	v_mfma_f32_32x32x16_bf16 v[68:83], v[108:111], v[0:3], v[68:83]
	v_mfma_f32_32x32x16_bf16 v[52:67], v[22:25], v[0:3], v[52:67]
	v_add_f32_e64 v0, v124, v126
	v_add_f32_e64 v1, v125, v127
	v_add_f32_e64 v2, v128, v130
	v_add_f32_e64 v3, v129, v131
	v_add_f32_e64 v0, v0, v2
	v_add_f32_e64 v1, v1, v3
	v_pk_add_f32 v[2:3], v[102:103], v[20:21]
	s_nop 0
	v_pk_add_f32 v[2:3], v[2:3], v[16:17]
	v_mfma_f32_32x32x16_bf16 v[36:51], v[8:11], v[4:7], v[36:51]
	v_add_f32_e64 v0, v0, v2
	v_add_f32_e64 v1, v1, v3
	v_add_f32_e64 v2, v132, v134
	v_add_f32_e64 v3, v133, v135
	v_add_f32_e64 v8, v136, v138
	v_add_f32_e64 v9, v137, v139
	v_pk_add_f32 v[10:11], v[120:121], v[30:31]
	v_pk_add_f32 v[2:3], v[2:3], v[8:9]
	v_pk_add_f32 v[8:9], v[140:141], v[142:143]
	v_mfma_f32_32x32x16_bf16 v[84:99], v[12:15], v[4:7], v[84:99]
	v_add_f32_e64 v8, v8, v10
	v_add_f32_e64 v9, v9, v11
	v_add_f32_e64 v2, v2, v8
	v_add_f32_e64 v3, v3, v9
	v_add_f32_e64 v0, v0, v2
	v_add_f32_e64 v1, v1, v3
	v_add_f32_e32 v0, v0, v1
	v_mfma_f32_32x32x16_bf16 v[68:83], v[26:29], v[4:7], v[68:83]
	v_add_f32_e32 v0, v0, v100
	v_mov_b32_e32 v1, v0
	v_mov_b32_e32 v2, v0
	s_nop 1
	v_permlane32_swap_b32_e32 v1, v2
	v_mfma_f32_32x32x16_bf16 v[52:67], v[116:119], v[4:7], v[52:67]
	s_and_saveexec_b64 s[0:1], vcc
	s_cbranch_execz .LBB0_127
	v_readlane_b32 s4, v254, 47
	s_nop 1
	v_mov_b32_e32 v3, s4
	ds_write_b32 v3, v197
